# v31 plus: tile-order integer division by the (always 8) group size seeded with a constant instead of the v_rcp/readfirstlane chain in every unit-loop header
# baseline (speedup 1.0000x reference)
;   __device__ __forceinline__ bool next(int i,AttnUnit&u)const{ if(i>=4)return false; const int s=vcu&7; u.bh=vcu>>3; u.qb=(i==0)?s:(i==1)?15-s:(i==2)?16+s:31-s; return true; }
;     __host__ __device__ bool next(int i, Unit& u) const {
;         const long L = (long)i * G + c; if (L >= nwg) return false;
;         int wgid = (int)L; { const int q = nwg / NXCD, r = nwg % NXCD, xcd = wgid % NXCD, off = wgid / NXCD; wgid = (xcd < r ? xcd * (q + 1) : r * (q + 1) + (xcd - r) * q) + off; }
;         const int nig = WGM * nN, gid = wgid / nig, fm = gid * WGM, gsz = (nM - fm) < WGM ? (nM - fm) : WGM;
;         u.pm = fm + ((wgid % nig) % gsz); u.pn = (wgid % nig) / gsz; return true;
.LBB0_229:
	s_add_i32 s53, s53, 1
	s_mul_i32 s4, s53, s56
	s_mul_hi_u32 s5, s53, s61
	s_add_i32 s5, s5, s4
	s_mul_i32 s4, s53, s61
	s_add_u32 s22, s4, s2
	s_addc_u32 s23, s5, s3
	v_cmp_gt_i64_e32 vcc, s[22:23], v[142:143]
	v_cmp_lt_i64_e64 s[4:5], s[22:23], v[140:141]
	s_cbranch_vccnz .LBB0_231
	s_ashr_i32 s18, s22, 31
	s_lshr_b32 s18, s18, 29
	s_add_i32 s18, s22, s18
	s_ashr_i32 s19, s18, 3
	s_and_b32 s18, s18, -8
	s_sub_i32 s18, s22, s18
	s_cmp_lt_i32 s18, 0
	s_cselect_b32 s20, s49, 0x160
	s_mul_i32 s18, s20, s18
	s_add_i32 s18, s18, s19
	s_mul_hi_i32 s19, s18, 0x2e8ba2e9
	s_lshr_b32 s20, s19, 31
	s_ashr_i32 s19, s19, 5
	s_add_i32 s19, s19, s20
	s_lshl_b32 s20, s19, 3
	s_sub_i32 s21, 0x80, s20
	s_min_i32 s21, s21, 8
	s_abs_i32 s22, s21
	s_sub_i32 s34, 0, s22
	s_mulk_i32 s19, 0xb0
	s_sub_i32 s19, s18, s19
	s_abs_i32 s18, s19
	s_xor_b32 s23, s19, s21
	s_ashr_i32 s23, s23, 31
	s_mov_b32 s35, 0x1fffffc0
	s_mul_i32 s34, s34, s35
	s_mul_hi_u32 s34, s35, s34
	s_add_i32 s35, s35, s34
	s_mul_hi_u32 s34, s18, s35
	s_mul_i32 s35, s34, s22
	s_sub_i32 s18, s18, s35
	s_add_i32 s42, s34, 1
	s_sub_i32 s35, s18, s22
	s_cmp_ge_u32 s18, s22
	s_cselect_b32 s34, s42, s34
	s_cselect_b32 s18, s35, s18
	s_add_i32 s35, s34, 1
	s_cmp_ge_u32 s18, s22
	s_cselect_b32 s18, s35, s34
	s_xor_b32 s18, s18, s23
	s_sub_i32 s18, s18, s23
	s_mul_i32 s21, s18, s21
	s_sub_i32 s19, s19, s21
	s_add_i32 s20, s19, s20

;     __host__ __device__ bool next(int i, Unit& u) const {
;         const long L = (long)i * G + c; if (L >= nwg) return false;
;         int wgid = (int)L; { const int q = nwg / NXCD, r = nwg % NXCD, xcd = wgid % NXCD, off = wgid / NXCD; wgid = (xcd < r ? xcd * (q + 1) : r * (q + 1) + (xcd - r) * q) + off; }
;         const int nig = WGM * nN, gid = wgid / nig, fm = gid * WGM, gsz = (nM - fm) < WGM ? (nM - fm) : WGM;
;         u.pm = fm + ((wgid % nig) % gsz); u.pn = (wgid % nig) / gsz; return true;
.LBB0_400:
	s_ashr_i32 s6, s22, 3
	s_add_i32 s6, s38, s6
	s_ashr_i32 s7, s6, 31
	s_lshr_b32 s7, s7, 27
	s_add_i32 s7, s6, s7
	s_ashr_i32 s22, s7, 5
	s_lshl_b32 s22, s22, 3
	s_sub_i32 s23, 0x80, s22
	s_min_i32 s23, s23, 8
	s_abs_i32 s38, s23
	s_sub_i32 s55, 0, s38
	s_andn2_b32 s7, s7, 31
	s_sub_i32 s6, s6, s7
	s_abs_i32 s7, s6
	s_xor_b32 s39, s6, s23
	s_ashr_i32 s39, s39, 31
	s_mov_b32 s56, 0x1fffffc0
	s_mul_i32 s55, s55, s56
	s_mul_hi_u32 s55, s56, s55
	s_add_i32 s56, s56, s55
	s_mul_hi_u32 s55, s7, s56
	s_mul_i32 s56, s55, s38
	s_sub_i32 s7, s7, s56
	s_add_i32 s59, s55, 1
	s_sub_i32 s56, s7, s38
	s_cmp_ge_u32 s7, s38
	s_cselect_b32 s55, s59, s55
	s_cselect_b32 s7, s56, s7
	s_add_i32 s56, s55, 1
	s_cmp_ge_u32 s7, s38
	s_cselect_b32 s7, s56, s55
	s_xor_b32 s7, s7, s39
	s_sub_i32 s55, s7, s39
	s_mul_i32 s7, s55, s23
	s_sub_i32 s6, s6, s7
	s_add_i32 s56, s22, s6

;   __device__ __forceinline__ bool next(int i,AttnUnit&u)const{ if(i>=4)return false; const int s=vcu&7; u.bh=vcu>>3; u.qb=(i==0)?s:(i==1)?15-s:(i==2)?16+s:31-s; return true; }
;     __host__ __device__ bool next(int i, Unit& u) const {
;         const long L = (long)i * G + c; if (L >= nwg) return false;
;         int wgid = (int)L; { const int q = nwg / NXCD, r = nwg % NXCD, xcd = wgid % NXCD, off = wgid / NXCD; wgid = (xcd < r ? xcd * (q + 1) : r * (q + 1) + (xcd - r) * q) + off; }
;         const int nig = WGM * nN, gid = wgid / nig, fm = gid * WGM, gsz = (nM - fm) < WGM ? (nM - fm) : WGM;
;         u.pm = fm + ((wgid % nig) % gsz); u.pn = (wgid % nig) / gsz; return true;
.LBB0_590:
	s_add_i32 s59, s59, 1
	s_mul_i32 s4, s59, s67
	s_mul_hi_u32 s5, s59, s61
	s_add_i32 s5, s5, s4
	s_mul_i32 s4, s59, s61
	s_add_u32 s38, s4, s2
	s_addc_u32 s39, s5, s3
	v_cmp_gt_i64_e32 vcc, s[38:39], v[142:143]
	v_cmp_lt_i64_e64 s[4:5], s[38:39], v[140:141]
	s_cbranch_vccnz .LBB0_592
	s_ashr_i32 s34, s38, 31
	s_lshr_b32 s34, s34, 29
	s_add_i32 s34, s38, s34
	s_ashr_i32 s35, s34, 3
	s_and_b32 s34, s34, -8
	s_sub_i32 s34, s38, s34
	s_cmp_lt_i32 s34, 0
	s_cselect_b32 s36, s55, 0xc0
	s_mul_i32 s34, s36, s34
	s_add_i32 s34, s34, s35
	s_mul_hi_i32 s35, s34, 0x2aaaaaab
	s_lshr_b32 s36, s35, 31
	s_ashr_i32 s35, s35, 4
	s_add_i32 s35, s35, s36
	s_lshl_b32 s36, s35, 3
	s_sub_i32 s37, 0x80, s36
	s_min_i32 s37, s37, 8
	s_abs_i32 s38, s37
	s_sub_i32 s40, 0, s38
	s_mulk_i32 s35, 0x60
	s_sub_i32 s35, s34, s35
	s_abs_i32 s34, s35
	s_xor_b32 s39, s35, s37
	s_ashr_i32 s39, s39, 31
	s_mov_b32 s41, 0x1fffffc0
	s_mul_i32 s40, s40, s41
	s_mul_hi_u32 s40, s41, s40
	s_add_i32 s41, s41, s40
	s_mul_hi_u32 s40, s34, s41
	s_mul_i32 s41, s40, s38
	s_sub_i32 s34, s34, s41
	s_add_i32 s48, s40, 1
	s_sub_i32 s41, s34, s38
	s_cmp_ge_u32 s34, s38
	s_cselect_b32 s40, s48, s40
	s_cselect_b32 s34, s41, s34
	s_add_i32 s41, s40, 1
	s_cmp_ge_u32 s34, s38
	s_cselect_b32 s34, s41, s40
	s_xor_b32 s34, s34, s39
	s_sub_i32 s34, s34, s39
	s_mul_i32 s37, s34, s37
	s_sub_i32 s35, s35, s37
	s_add_i32 s36, s35, s36

;     __host__ __device__ bool next(int i, Unit& u) const {
;         const long L = (long)i * G + c; if (L >= nwg) return false;
;         int wgid = (int)L; { const int q = nwg / NXCD, r = nwg % NXCD, xcd = wgid % NXCD, off = wgid / NXCD; wgid = (xcd < r ? xcd * (q + 1) : r * (q + 1) + (xcd - r) * q) + off; }
;         const int nig = WGM * nN, gid = wgid / nig, fm = gid * WGM, gsz = (nM - fm) < WGM ? (nM - fm) : WGM;
;         u.pm = fm + ((wgid % nig) % gsz); u.pn = (wgid % nig) / gsz; return true;
.LBB0_1010:
	s_ashr_i32 s20, s22, 3
	s_add_i32 s20, s34, s20
	s_ashr_i32 s21, s20, 31
	s_lshr_b32 s21, s21, 27
	s_add_i32 s21, s20, s21
	s_ashr_i32 s22, s21, 5
	s_lshl_b32 s22, s22, 3
	s_sub_i32 s23, 0x80, s22
	s_min_i32 s23, s23, 8
	s_abs_i32 s34, s23
	s_sub_i32 s36, 0, s34
	s_andn2_b32 s21, s21, 31
	s_sub_i32 s21, s20, s21
	s_abs_i32 s20, s21
	s_xor_b32 s35, s21, s23
	s_ashr_i32 s35, s35, 31
	s_mov_b32 s37, 0x1fffffc0
	s_mul_i32 s36, s36, s37
	s_mul_hi_u32 s36, s37, s36
	s_add_i32 s37, s37, s36
	s_mul_hi_u32 s36, s20, s37
	s_mul_i32 s37, s36, s34
	s_sub_i32 s20, s20, s37
	s_add_i32 s39, s36, 1
	s_sub_i32 s37, s20, s34
	s_cmp_ge_u32 s20, s34
	s_cselect_b32 s36, s39, s36
	s_cselect_b32 s20, s37, s20
	s_add_i32 s37, s36, 1
	s_cmp_ge_u32 s20, s34
	s_cselect_b32 s20, s37, s36
	s_xor_b32 s20, s20, s35
	s_sub_i32 s20, s20, s35
	s_mul_i32 s23, s20, s23
	s_sub_i32 s21, s21, s23
	s_add_i32 s22, s22, s21

;   __device__ __forceinline__ bool next(int i,AttnUnit&u)const{ if(i>=4)return false; const int s=vcu&7; u.bh=vcu>>3; u.qb=(i==0)?s:(i==1)?15-s:(i==2)?16+s:31-s; return true; }
;     __host__ __device__ bool next(int i, Unit& u) const {
;         const long L = (long)i * G + c; if (L >= nwg) return false;
;         int wgid = (int)L; { const int q = nwg / NXCD, r = nwg % NXCD, xcd = wgid % NXCD, off = wgid / NXCD; wgid = (xcd < r ? xcd * (q + 1) : r * (q + 1) + (xcd - r) * q) + off; }
;         const int nig = WGM * nN, gid = wgid / nig, fm = gid * WGM, gsz = (nM - fm) < WGM ? (nM - fm) : WGM;
;         u.pm = fm + ((wgid % nig) % gsz); u.pn = (wgid % nig) / gsz; return true;
.LBB0_1191:
	s_add_i32 s55, s55, 1
	s_mul_i32 s4, s55, s56
	s_mul_hi_u32 s5, s55, s61
	s_add_i32 s5, s5, s4
	s_mul_i32 s4, s55, s61
	s_add_u32 s22, s4, s2
	s_addc_u32 s23, s5, s3
	v_cmp_gt_i64_e32 vcc, s[22:23], v[142:143]
	v_cmp_lt_i64_e64 s[4:5], s[22:23], v[140:141]
	s_cbranch_vccnz .LBB0_1193
	s_ashr_i32 s18, s22, 31
	s_lshr_b32 s18, s18, 29
	s_add_i32 s18, s22, s18
	s_ashr_i32 s19, s18, 3
	s_and_b32 s18, s18, -8
	s_sub_i32 s18, s22, s18
	s_cmp_lt_i32 s18, 0
	s_cselect_b32 s20, s49, 0x160
	s_mul_i32 s18, s20, s18
	s_add_i32 s18, s18, s19
	s_mul_hi_i32 s19, s18, 0x2e8ba2e9
	s_lshr_b32 s20, s19, 31
	s_ashr_i32 s19, s19, 5
	s_add_i32 s19, s19, s20
	s_lshl_b32 s20, s19, 3
	s_sub_i32 s21, 0x80, s20
	s_min_i32 s21, s21, 8
	s_abs_i32 s22, s21
	s_sub_i32 s34, 0, s22
	s_mulk_i32 s19, 0xb0
	s_sub_i32 s19, s18, s19
	s_abs_i32 s18, s19
	s_xor_b32 s23, s19, s21
	s_ashr_i32 s23, s23, 31
	s_mov_b32 s35, 0x1fffffc0
	s_mul_i32 s34, s34, s35
	s_mul_hi_u32 s34, s35, s34
	s_add_i32 s35, s35, s34
	s_mul_hi_u32 s34, s18, s35
	s_mul_i32 s35, s34, s22
	s_sub_i32 s18, s18, s35
	s_add_i32 s42, s34, 1
	s_sub_i32 s35, s18, s22
	s_cmp_ge_u32 s18, s22
	s_cselect_b32 s34, s42, s34
	s_cselect_b32 s18, s35, s18
	s_add_i32 s35, s34, 1
	s_cmp_ge_u32 s18, s22
	s_cselect_b32 s18, s35, s34
	s_xor_b32 s18, s18, s23
	s_sub_i32 s18, s18, s23
	s_mul_i32 s21, s18, s21
	s_sub_i32 s19, s19, s21
	s_add_i32 s20, s19, s20

;   __device__ __forceinline__ bool next(int i,AttnUnit&u)const{ if(i>=4)return false; const int s=vcu&7; u.bh=vcu>>3; u.qb=(i==0)?s:(i==1)?15-s:(i==2)?16+s:31-s; return true; }
;     __host__ __device__ bool next(int i, Unit& u) const {
;         const long L = (long)i * G + c; if (L >= nwg) return false;
;         int wgid = (int)L; { const int q = nwg / NXCD, r = nwg % NXCD, xcd = wgid % NXCD, off = wgid / NXCD; wgid = (xcd < r ? xcd * (q + 1) : r * (q + 1) + (xcd - r) * q) + off; }
;         const int nig = WGM * nN, gid = wgid / nig, fm = gid * WGM, gsz = (nM - fm) < WGM ? (nM - fm) : WGM;
;         u.pm = fm + ((wgid % nig) % gsz); u.pn = (wgid % nig) / gsz; return true;
.LBB0_1903:
	s_add_i32 s55, s55, 1
	s_mul_i32 s4, s55, s56
	s_mul_hi_u32 s5, s55, s61
	s_add_i32 s5, s5, s4
	s_mul_i32 s4, s55, s61
	s_add_u32 s22, s4, s2
	s_addc_u32 s23, s5, s3
	v_cmp_gt_i64_e32 vcc, s[22:23], v[142:143]
	v_cmp_lt_i64_e64 s[4:5], s[22:23], v[140:141]
	s_cbranch_vccnz .LBB0_1905
	s_ashr_i32 s18, s22, 31
	s_lshr_b32 s18, s18, 29
	s_add_i32 s18, s22, s18
	s_ashr_i32 s19, s18, 3
	s_and_b32 s18, s18, -8
	s_sub_i32 s18, s22, s18
	s_cmp_lt_i32 s18, 0
	s_cselect_b32 s20, s49, 0x50
	s_mul_i32 s18, s20, s18
	s_add_i32 s18, s18, s19
	s_mul_hi_i32 s19, s18, 0x66666667
	s_lshr_b32 s20, s19, 31
	s_ashr_i32 s19, s19, 4
	s_add_i32 s19, s19, s20
	s_lshl_b32 s20, s19, 3
	s_sub_i32 s21, 0x80, s20
	s_min_i32 s21, s21, 8
	s_abs_i32 s22, s21
	s_sub_i32 s34, 0, s22
	s_mul_i32 s19, s19, 40
	s_sub_i32 s19, s18, s19
	s_abs_i32 s18, s19
	s_xor_b32 s23, s19, s21
	s_ashr_i32 s23, s23, 31
	s_mov_b32 s35, 0x1fffffc0
	s_mul_i32 s34, s34, s35
	s_mul_hi_u32 s34, s35, s34
	s_add_i32 s35, s35, s34
	s_mul_hi_u32 s34, s18, s35
	s_mul_i32 s35, s34, s22
	s_sub_i32 s18, s18, s35
	s_add_i32 s42, s34, 1
	s_sub_i32 s35, s18, s22
	s_cmp_ge_u32 s18, s22
	s_cselect_b32 s34, s42, s34
	s_cselect_b32 s18, s35, s18
	s_add_i32 s35, s34, 1
	s_cmp_ge_u32 s18, s22
	s_cselect_b32 s18, s35, s34
	s_xor_b32 s18, s18, s23
	s_sub_i32 s18, s18, s23
	s_mul_i32 s21, s18, s21
	s_sub_i32 s19, s19, s21
	s_add_i32 s20, s19, s20

;     __host__ __device__ bool next(int i, Unit& u) const {
;         const long L = (long)i * G + c; if (L >= nwg) return false;
;         int wgid = (int)L; { const int q = nwg / NXCD, r = nwg % NXCD, xcd = wgid % NXCD, off = wgid / NXCD; wgid = (xcd < r ? xcd * (q + 1) : r * (q + 1) + (xcd - r) * q) + off; }
;         const int nig = WGM * nN, gid = wgid / nig, fm = gid * WGM, gsz = (nM - fm) < WGM ? (nM - fm) : WGM;
;         u.pm = fm + ((wgid % nig) % gsz); u.pn = (wgid % nig) / gsz; return true;
.LBB0_2591:
	s_ashr_i32 s4, s36, 3
	s_add_i32 s4, s42, s4
	s_ashr_i32 s5, s4, 31
	s_lshr_b32 s5, s5, 27
	s_add_i32 s5, s4, s5
	s_ashr_i32 s36, s5, 5
	s_lshl_b32 s36, s36, 3
	s_sub_i32 s37, 0x80, s36
	s_min_i32 s37, s37, 8
	s_abs_i32 s42, s37
	s_sub_i32 s59, 0, s42
	s_andn2_b32 s5, s5, 31
	s_sub_i32 s4, s4, s5
	s_abs_i32 s5, s4
	s_xor_b32 s43, s4, s37
	s_ashr_i32 s43, s43, 31
	s_mov_b32 s63, 0x1fffffc0
	s_mul_i32 s59, s59, s63
	s_mul_hi_u32 s59, s63, s59
	s_add_i32 s63, s63, s59
	s_mul_hi_u32 s59, s5, s63
	s_mul_i32 s63, s59, s42
	s_sub_i32 s5, s5, s63
	s_add_i32 s66, s59, 1
	s_sub_i32 s63, s5, s42
	s_cmp_ge_u32 s5, s42
	s_cselect_b32 s59, s66, s59
	s_cselect_b32 s5, s63, s5
	s_add_i32 s63, s59, 1
	s_cmp_ge_u32 s5, s42
	s_cselect_b32 s5, s63, s59
	s_xor_b32 s5, s5, s43
	s_sub_i32 s59, s5, s43
	s_mul_i32 s5, s59, s37
	s_sub_i32 s4, s4, s5
	s_add_i32 s63, s36, s4
